# counted vmcnt for the two V staging writes (vmcnt(1) before the first, vmcnt(0) before the second) instead of one vmcnt(0) after barrier 1
# baseline (speedup 1.0000x reference)
; __device__ __forceinline__ void partialSM(f32x16& p0, f32x16& p1, float& m_reg, float& mn, float& alpha) {
;     float pmax = p0[0]; for (int r = 1; r < 16; ++r) pmax = fmaxf(pmax, p0[r]); for (int r = 0; r < 16; ++r) pmax = fmaxf(pmax, p1[r]);
;     { auto rr = __builtin_amdgcn_permlane32_swap(__float_as_uint(pmax), __float_as_uint(pmax), false, false);
;       pmax = fmaxf(__uint_as_float(rr[0]), __uint_as_float(rr[1])); }
;     constexpr float C2 = 1.4426950408889634f * SCALE;
;     if (__builtin_expect(__all((pmax - m_reg) * SCALE <= THR), 1)) { mn = m_reg; alpha = 1.f; }
;     else { mn = fmaxf(m_reg, pmax); alpha = __builtin_amdgcn_exp2f((m_reg - mn) * C2); m_reg = mn; }
;     const float mnL = -mn * C2;
;     for (int r = 0; r < 16; ++r) p0[r] = fmaf(p0[r], C2, mnL); for (int r = 0; r < 16; ++r) p1[r] = fmaf(p1[r], C2, mnL);
;     for (int r = 0; r < 16; ++r) p0[r] = __builtin_amdgcn_exp2f(p0[r]);
; }
; __device__ __forceinline__ void finishSM(f32x16& p0, f32x16& p1, float alpha, float& l_reg, bf16x8& pa0, bf16x8& pa1, bf16x8& pa2, bf16x8& pa3) {
;     for (int r = 0; r < 16; ++r) p1[r] = __builtin_amdgcn_exp2f(p1[r]);
;     float ps = 0; for (int r = 0; r < 16; ++r) ps += p0[r]; for (int r = 0; r < 16; ++r) ps += p1[r];
;     { auto rr = __builtin_amdgcn_permlane32_swap(__float_as_uint(ps), __float_as_uint(ps), false, false);
;       ps = __uint_as_float(rr[0]) + __uint_as_float(rr[1]); }
;     l_reg = l_reg * alpha + ps;
;     ...
;     PK4(p0, 0, pa0); PK4(p0, 8, pa1); PK4(p1, 0, pa2); PK4(p1, 8, pa3);
;     ...
; }
; template <int KB, bool SK>
; __device__ __forceinline__ void qkt(f32x16& p0, f32x16& p1, const char* K_lds, int r32, int hi, const bf16x8* qr, bool act) {
;     if (SK && !act) { const float NEG = -__builtin_inff();
; #pragma unroll
;         for (int r = 0; r < 16; ++r) { p0[r] = NEG; p1[r] = NEG; } return; }
;     p0 = f32x16{}; p1 = f32x16{};
;     const char* kb[4];
; #pragma unroll
;     for (int dd = 0; dd < 4; ++dd) kb[dd] = K_lds + KB * SHM_K + KSWZ(r32, (dd * 16 + hi * 8) * 2);
; #pragma unroll
;     for (int d0 = 0; d0 < 8; ++d0) { const char* a = kb[d0 & 3] + (d0 >> 2) * 128;
;         bf16x8 b0 = *reinterpret_cast<const bf16x8*>(a);
;         bf16x8 b1 = *reinterpret_cast<const bf16x8*>(a + 32 * 256);
;         const bf16x8 qf = qr[d0];
;         p0 = __builtin_amdgcn_mfma_f32_32x32x16_bf16(b0, qf, p0, 0, 0, 0);
.Lh1_back:
	v_fmamk_f32 v228, v86, 0x3e0293ee, v253
	v_fmamk_f32 v229, v87, 0x3e0293ee, v253
	s_waitcnt lgkmcnt(12)
	v_mfma_f32_32x32x16_bf16 v[50:65], v[66:69], v[186:189], v[50:65]
	ds_read_b64_tr_b16 v[182:183], v202 offset:0x600
	ds_read_b64_tr_b16 v[184:185], v202 offset:0xe00
	v_fmamk_f32 v230, v88, 0x3e0293ee, v253
	v_fmamk_f32 v231, v89, 0x3e0293ee, v253
	v_fmamk_f32 v232, v90, 0x3e0293ee, v253
	s_waitcnt lgkmcnt(12)
	v_mfma_f32_32x32x16_bf16 v[50:65], v[106:109], v[190:193], v[50:65]
	ds_read_b64_tr_b16 v[186:187], v202 offset:0x1600
	ds_read_b64_tr_b16 v[188:189], v202 offset:0x1e00
	v_fmamk_f32 v233, v91, 0x3e0293ee, v253
	v_fmamk_f32 v234, v92, 0x3e0293ee, v253
	v_fmamk_f32 v235, v93, 0x3e0293ee, v253
	s_waitcnt lgkmcnt(12)
	v_mfma_f32_32x32x16_bf16 v[50:65], v[110:113], v[244:247], v[50:65]
	ds_read_b64_tr_b16 v[190:191], v202 offset:0x2600
	ds_read_b64_tr_b16 v[192:193], v202 offset:0x2e00
	v_fmamk_f32 v236, v94, 0x3e0293ee, v253
	v_fmamk_f32 v237, v95, 0x3e0293ee, v253
	v_fmamk_f32 v238, v96, 0x3e0293ee, v253
	s_waitcnt lgkmcnt(12)
	v_mfma_f32_32x32x16_bf16 v[18:33], v[102:105], v[114:117], v[18:33]
	ds_read_b64_tr_b16 v[244:245], v202 offset:0x3600
	ds_read_b64_tr_b16 v[246:247], v202 offset:0x3e00
	v_fmamk_f32 v239, v97, 0x3e0293ee, v253
	v_fmamk_f32 v98, v98, 0x3e0293ee, v253
	v_fmamk_f32 v99, v99, 0x3e0293ee, v253
	s_waitcnt lgkmcnt(12)
	v_mfma_f32_32x32x16_bf16 v[18:33], v[66:69], v[118:121], v[18:33]
	v_fmamk_f32 v100, v100, 0x3e0293ee, v253
	v_fmamk_f32 v101, v101, 0x3e0293ee, v253
	v_fmamk_f32 v86, v70, 0x3e0293ee, v253
	s_waitcnt lgkmcnt(10)
	v_mfma_f32_32x32x16_bf16 v[18:33], v[106:109], v[122:125], v[18:33]
	v_fmamk_f32 v95, v71, 0x3e0293ee, v253
	v_fmamk_f32 v96, v72, 0x3e0293ee, v253
	v_fmamk_f32 v97, v73, 0x3e0293ee, v253
	s_waitcnt lgkmcnt(8)
	v_mfma_f32_32x32x16_bf16 v[18:33], v[110:113], v[126:129], v[18:33]
	v_fmamk_f32 v179, v74, 0x3e0293ee, v253
	v_fmamk_f32 v87, v75, 0x3e0293ee, v253
	v_fmamk_f32 v88, v76, 0x3e0293ee, v253
	s_waitcnt lgkmcnt(0)
	s_barrier
	s_waitcnt vmcnt(1)
	v_mfma_f32_32x32x16_bf16 v[2:17], v[102:105], v[182:185], v[2:17]
	ds_write_b128 v209, v[162:165]
	v_fmamk_f32 v89, v77, 0x3e0293ee, v253
	v_fmamk_f32 v90, v78, 0x3e0293ee, v253
	v_fmamk_f32 v91, v79, 0x3e0293ee, v253
	v_mfma_f32_32x32x16_bf16 v[2:17], v[66:69], v[186:189], v[2:17]
	s_waitcnt vmcnt(0)
	ds_write_b128 v210, v[166:169]
	v_fmamk_f32 v92, v80, 0x3e0293ee, v253
	v_fmamk_f32 v93, v81, 0x3e0293ee, v253
	v_fmamk_f32 v94, v82, 0x3e0293ee, v253
	v_mfma_f32_32x32x16_bf16 v[2:17], v[106:109], v[190:193], v[2:17]
	v_fmamk_f32 v180, v83, 0x3e0293ee, v253
	v_fmamk_f32 v181, v84, 0x3e0293ee, v253
	v_fmamk_f32 v178, v85, 0x3e0293ee, v253
	v_mfma_f32_32x32x16_bf16 v[2:17], v[110:113], v[244:247], v[2:17]
	s_and_b64 vcc, exec, s[4:5]
	s_cbranch_vccnz .Lh1_noresc
	s_and_saveexec_b64 s[52:53], s[0:1]
	ds_write_b32 v219, v225 offset:128
	s_or_b64 exec, exec, s[52:53]
	s_waitcnt lgkmcnt(0)
	ds_read_b128 v[102:105], v218 offset:224
	ds_read_b128 v[106:109], v218 offset:192
	ds_read_b128 v[110:113], v218 offset:160
	ds_read_b128 v[114:117], v218 offset:128
	s_waitcnt lgkmcnt(3)
	v_pk_mul_f32 v[48:49], v[48:49], v[104:105]
	s_waitcnt lgkmcnt(2)
	v_pk_mul_f32 v[44:45], v[44:45], v[108:109]
	s_waitcnt lgkmcnt(1)
	v_pk_mul_f32 v[40:41], v[40:41], v[112:113]
	s_waitcnt lgkmcnt(0)
	v_pk_mul_f32 v[36:37], v[36:37], v[116:117]
	v_pk_mul_f32 v[46:47], v[46:47], v[102:103]
	v_pk_mul_f32 v[42:43], v[42:43], v[106:107]
	v_pk_mul_f32 v[38:39], v[38:39], v[110:111]
	v_pk_mul_f32 v[34:35], v[34:35], v[114:115]
	v_pk_mul_f32 v[64:65], v[64:65], v[104:105]
	v_pk_mul_f32 v[60:61], v[60:61], v[108:109]
	v_pk_mul_f32 v[56:57], v[56:57], v[112:113]
	v_pk_mul_f32 v[52:53], v[52:53], v[116:117]
	v_pk_mul_f32 v[62:63], v[62:63], v[102:103]
	v_pk_mul_f32 v[58:59], v[58:59], v[106:107]
	v_pk_mul_f32 v[54:55], v[54:55], v[110:111]
	v_pk_mul_f32 v[50:51], v[50:51], v[114:115]
	v_pk_mul_f32 v[32:33], v[32:33], v[104:105]
	v_pk_mul_f32 v[28:29], v[28:29], v[108:109]
	v_pk_mul_f32 v[24:25], v[24:25], v[112:113]
	v_pk_mul_f32 v[20:21], v[20:21], v[116:117]
	v_pk_mul_f32 v[30:31], v[30:31], v[102:103]
	v_pk_mul_f32 v[26:27], v[26:27], v[106:107]
	v_pk_mul_f32 v[22:23], v[22:23], v[110:111]
	v_pk_mul_f32 v[18:19], v[18:19], v[114:115]
	v_pk_mul_f32 v[16:17], v[16:17], v[104:105]
	v_pk_mul_f32 v[12:13], v[12:13], v[108:109]
	v_pk_mul_f32 v[8:9], v[8:9], v[112:113]
	v_pk_mul_f32 v[4:5], v[4:5], v[116:117]
	v_pk_mul_f32 v[14:15], v[14:15], v[102:103]
	v_pk_mul_f32 v[10:11], v[10:11], v[106:107]
	v_pk_mul_f32 v[6:7], v[6:7], v[110:111]
	v_pk_mul_f32 v[2:3], v[2:3], v[114:115]

; __device__ __forceinline__ void partialSM(f32x16& p0, f32x16& p1, float& m_reg, float& mn, float& alpha) {
;     float pmax = p0[0]; for (int r = 1; r < 16; ++r) pmax = fmaxf(pmax, p0[r]); for (int r = 0; r < 16; ++r) pmax = fmaxf(pmax, p1[r]);
;     { auto rr = __builtin_amdgcn_permlane32_swap(__float_as_uint(pmax), __float_as_uint(pmax), false, false);
;       pmax = fmaxf(__uint_as_float(rr[0]), __uint_as_float(rr[1])); }
;     constexpr float C2 = 1.4426950408889634f * SCALE;
;     if (__builtin_expect(__all((pmax - m_reg) * SCALE <= THR), 1)) { mn = m_reg; alpha = 1.f; }
;     else { mn = fmaxf(m_reg, pmax); alpha = __builtin_amdgcn_exp2f((m_reg - mn) * C2); m_reg = mn; }
;     const float mnL = -mn * C2;
;     for (int r = 0; r < 16; ++r) p0[r] = fmaf(p0[r], C2, mnL); for (int r = 0; r < 16; ++r) p1[r] = fmaf(p1[r], C2, mnL);
;     for (int r = 0; r < 16; ++r) p0[r] = __builtin_amdgcn_exp2f(p0[r]);
; }
; __device__ __forceinline__ void finishSM(f32x16& p0, f32x16& p1, float alpha, float& l_reg, bf16x8& pa0, bf16x8& pa1, bf16x8& pa2, bf16x8& pa3) {
;     for (int r = 0; r < 16; ++r) p1[r] = __builtin_amdgcn_exp2f(p1[r]);
;     float ps = 0; for (int r = 0; r < 16; ++r) ps += p0[r]; for (int r = 0; r < 16; ++r) ps += p1[r];
;     { auto rr = __builtin_amdgcn_permlane32_swap(__float_as_uint(ps), __float_as_uint(ps), false, false);
;       ps = __uint_as_float(rr[0]) + __uint_as_float(rr[1]); }
;     l_reg = l_reg * alpha + ps;
;     ...
;     PK4(p0, 0, pa0); PK4(p0, 8, pa1); PK4(p1, 0, pa2); PK4(p1, 8, pa3);
;     ...
; }
; template <int KB, bool SK>
; __device__ __forceinline__ void qkt(f32x16& p0, f32x16& p1, const char* K_lds, int r32, int hi, const bf16x8* qr, bool act) {
;     if (SK && !act) { const float NEG = -__builtin_inff();
; #pragma unroll
;         for (int r = 0; r < 16; ++r) { p0[r] = NEG; p1[r] = NEG; } return; }
;     p0 = f32x16{}; p1 = f32x16{};
;     const char* kb[4];
; #pragma unroll
;     for (int dd = 0; dd < 4; ++dd) kb[dd] = K_lds + KB * SHM_K + KSWZ(r32, (dd * 16 + hi * 8) * 2);
; #pragma unroll
;     for (int d0 = 0; d0 < 8; ++d0) { const char* a = kb[d0 & 3] + (d0 >> 2) * 128;
;         bf16x8 b0 = *reinterpret_cast<const bf16x8*>(a);
;         bf16x8 b1 = *reinterpret_cast<const bf16x8*>(a + 32 * 256);
;         const bf16x8 qf = qr[d0];
;         p0 = __builtin_amdgcn_mfma_f32_32x32x16_bf16(b0, qf, p0, 0, 0, 0);
.Lh2_back:
	v_fmamk_f32 v68, v114, 0x3e0293ee, v253
	v_fmamk_f32 v69, v115, 0x3e0293ee, v253
	s_waitcnt lgkmcnt(12)
	v_mfma_f32_32x32x16_bf16 v[50:65], v[182:185], v[90:93], v[50:65]
	ds_read_b64_tr_b16 v[86:87], v202 offset:0x4600
	ds_read_b64_tr_b16 v[88:89], v202 offset:0x4e00
	v_fmamk_f32 v70, v116, 0x3e0293ee, v253
	v_fmamk_f32 v71, v117, 0x3e0293ee, v253
	v_fmamk_f32 v79, v118, 0x3e0293ee, v253
	v_fmamk_f32 v80, v119, 0x3e0293ee, v253
	s_waitcnt lgkmcnt(12)
	v_mfma_f32_32x32x16_bf16 v[50:65], v[186:189], v[94:97], v[50:65]
	ds_read_b64_tr_b16 v[90:91], v202 offset:0x5600
	ds_read_b64_tr_b16 v[92:93], v202 offset:0x5e00
	v_fmamk_f32 v72, v120, 0x3e0293ee, v253
	v_fmamk_f32 v73, v121, 0x3e0293ee, v253
	v_fmamk_f32 v81, v122, 0x3e0293ee, v253
	v_fmamk_f32 v82, v123, 0x3e0293ee, v253
	s_waitcnt lgkmcnt(12)
	v_mfma_f32_32x32x16_bf16 v[50:65], v[190:193], v[246:249], v[50:65]
	ds_read_b64_tr_b16 v[94:95], v202 offset:0x6600
	ds_read_b64_tr_b16 v[96:97], v202 offset:0x6e00
	v_fmamk_f32 v74, v124, 0x3e0293ee, v253
	v_fmamk_f32 v75, v125, 0x3e0293ee, v253
	v_fmamk_f32 v76, v126, 0x3e0293ee, v253
	v_fmamk_f32 v77, v127, 0x3e0293ee, v253
	s_waitcnt lgkmcnt(12)
	v_mfma_f32_32x32x16_bf16 v[18:33], v[178:181], v[230:233], v[18:33]
	ds_read_b64_tr_b16 v[246:247], v202 offset:0x7600
	ds_read_b64_tr_b16 v[248:249], v202 offset:0x7e00
	v_fmamk_f32 v83, v128, 0x3e0293ee, v253
	v_fmamk_f32 v78, v129, 0x3e0293ee, v253
	v_fmamk_f32 v126, v98, 0x3e0293ee, v253
	v_fmamk_f32 v127, v99, 0x3e0293ee, v253
	s_waitcnt lgkmcnt(12)
	v_mfma_f32_32x32x16_bf16 v[18:33], v[182:185], v[234:237], v[18:33]
	v_fmamk_f32 v124, v100, 0x3e0293ee, v253
	v_fmamk_f32 v125, v101, 0x3e0293ee, v253
	v_fmamk_f32 v120, v102, 0x3e0293ee, v253
	s_waitcnt lgkmcnt(10)
	v_mfma_f32_32x32x16_bf16 v[18:33], v[186:189], v[238:241], v[18:33]
	v_fmamk_f32 v121, v103, 0x3e0293ee, v253
	v_fmamk_f32 v116, v104, 0x3e0293ee, v253
	v_fmamk_f32 v117, v105, 0x3e0293ee, v253
	s_waitcnt lgkmcnt(8)
	v_mfma_f32_32x32x16_bf16 v[18:33], v[190:193], v[242:245], v[18:33]
	v_fmamk_f32 v114, v106, 0x3e0293ee, v253
	v_fmamk_f32 v115, v107, 0x3e0293ee, v253
	v_fmamk_f32 v128, v108, 0x3e0293ee, v253
	s_waitcnt lgkmcnt(0)
	s_andn2_b64 vcc, exec, s[76:77]
	s_barrier
	s_cbranch_vccnz .Lh2_pvt_nowrite
	s_waitcnt vmcnt(1)
	v_mfma_f32_32x32x16_bf16 v[2:17], v[178:181], v[86:89], v[2:17]
	ds_write_b128 v209, v[162:165] offset:16384
	v_fmamk_f32 v129, v109, 0x3e0293ee, v253
	v_fmamk_f32 v122, v110, 0x3e0293ee, v253
	v_fmamk_f32 v123, v111, 0x3e0293ee, v253
	v_mfma_f32_32x32x16_bf16 v[2:17], v[182:185], v[90:93], v[2:17]
	s_waitcnt vmcnt(0)
	ds_write_b128 v210, v[166:169] offset:16384
	v_fmamk_f32 v118, v112, 0x3e0293ee, v253
	v_fmamk_f32 v119, v113, 0x3e0293ee, v253
	v_add_f32_e32 v98, v223, v224
	v_mfma_f32_32x32x16_bf16 v[2:17], v[186:189], v[94:97], v[2:17]
	v_fmac_f32_e32 v98, v197, v221
	v_add_f32_e32 v221, v228, v229
	v_fmac_f32_e32 v221, v98, v225
	v_mfma_f32_32x32x16_bf16 v[2:17], v[190:193], v[246:249], v[2:17]
	s_branch .Lh2_pvt_join
